# leader issues buffer_wbl2 before its L1 invalidate (leader test hoisted ahead of inv block), pad nop removed to keep later code offsets
# baseline (speedup 1.0000x reference)
; #define LAS __attribute__((address_space(3)))
; __global__ void __launch_bounds__(NTHR, 2) mega(P p, int ph_lo, int ph_hi) {
;     ...
;   __shared__ uint4 xb_words;
;   if (threadIdx.x == 0) xb_words = make_uint4(0u, 0u, 0u, 0u);
;   __syncthreads();
;   XcdBarrier xb; xb.bar = p.bar; xb.x = 0; xb.st = (volatile LAS unsigned*)&xb_words;
;   if (blockIdx.x == 0) { for (int i = threadIdx.x; i < XCD_BAR_WORDS; i += NTHR) p.bar[i] = 0u; }
.LBB0_2:
	s_or_b64 exec, exec, s[2:3]
	s_mov_b32 s2, 0
	s_nop 0
	v_writelane_b32 v229, s2, 55
	v_writelane_b32 v229, s2, 56
	s_nop 0
	s_nop 0
	s_nop 0
	s_nop 0
	s_nop 0
	s_nop 0
	s_nop 0
	s_nop 0
	s_mov_b32 s2, 0
	s_nop 0
	v_writelane_b32 v229, s2, 58
	v_writelane_b32 v229, s2, 59
	v_writelane_b32 v229, s2, 60
	s_load_dwordx2 s[82:83], s[0:1], 0x898
	s_load_dwordx2 s[34:35], s[0:1], 0x230
	v_readlane_b32 s2, v230, 0
	s_cmp_lg_u32 s2, 0
	s_waitcnt lgkmcnt(0)
	s_barrier
	s_cbranch_scc0 .LBB0_4
	s_load_dwordx2 s[8:9], s[0:1], 0x890
	s_waitcnt lgkmcnt(0)
	s_cmp_ge_i32 s8, s9
	s_cbranch_scc0 .LBB0_11
	s_getpc_b64 s[98:99]

; __device__ __forceinline__ unsigned xb_add(unsigned* p, unsigned v) { return __hip_atomic_fetch_add(p, v, __ATOMIC_RELAXED, __HIP_MEMORY_SCOPE_AGENT); }
; __device__ __forceinline__ void xcd_barrier(const XcdBarrier& b) {
;     ...
;     const unsigned old = xb_add(&bar[XB_XSUB(b.x)], 1u);
;     const unsigned gen = old / nloc;
;     if (old + 1u == (gen + 1u) * nloc) {
;       __builtin_amdgcn_fence(__ATOMIC_RELEASE, "agent");
;       asm volatile("s_waitcnt vmcnt(0)" ::: "memory");
.Lxb_nocu:
	v_cvt_f32_u32_e32 v1, v2
	v_sub_u32_e32 v4, 0, v2
	v_rcp_iflag_f32_e32 v1, v1
	s_nop 0
	v_mul_f32_e32 v1, 0x4f7ffffe, v1
	v_cvt_u32_f32_e32 v1, v1
	v_mul_lo_u32 v4, v4, v1
	v_mul_hi_u32 v4, v1, v4
	v_add_u32_e32 v1, v1, v4
	s_waitcnt vmcnt(0)
	v_mul_hi_u32 v1, v3, v1
	v_mul_lo_u32 v4, v1, v2
	v_sub_u32_e32 v4, v3, v4
	v_add_u32_e32 v5, 1, v1
	v_cmp_ge_u32_e32 vcc, v4, v2
	v_add_u32_e32 v3, 1, v3
	s_nop 0
	v_cndmask_b32_e32 v1, v1, v5, vcc
	v_sub_u32_e32 v5, v4, v2
	v_cndmask_b32_e32 v4, v4, v5, vcc
	v_add_u32_e32 v5, 1, v1
	v_cmp_ge_u32_e32 vcc, v4, v2
	s_nop 1
	v_cndmask_b32_e32 v1, v1, v5, vcc
	v_mul_lo_u32 v4, v2, v1
	v_add_u32_e32 v2, v4, v2
	v_cmp_ne_u32_e32 vcc, v3, v2
	s_cbranch_vccnz .Lxb_notlead
	buffer_wbl2 sc1
.Lxb_notlead:
	v_readfirstlane_b32 s14, v8
	s_nop 3
	s_and_b32 s14, s14, 0xffff
	s_cmp_lg_u32 s14, s13
	s_cbranch_scc1 .Lxb_skipinv
	buffer_inv sc1
.Lxb_skipinv:
	v_readlane_b32 s14, v229, 59
	s_nop 3
	s_add_u32 s13, s13, s14
	s_nop 0
	v_writelane_b32 v229, s13, 60
	s_and_saveexec_b64 s[10:11], vcc
	s_xor_b64 s[10:11], exec, s[10:11]
	s_cbranch_execz .LBB0_46
	s_waitcnt lgkmcnt(0)
	s_waitcnt vmcnt(0)
	global_atomic_add v198, v199, s[8:9] offset:1152
	global_load_dword v0, v200, s[8:9] offset:1024 sc1
	s_add_u32 s14, s8, 0x2400
	s_addc_u32 s15, s9, 0
	s_waitcnt vmcnt(0)
	v_cmp_eq_u32_e32 vcc, v0, v1
	s_and_saveexec_b64 s[12:13], vcc
	s_cbranch_execz .LBB0_45
	s_mov_b32 s4, 1
	s_mov_b64 s[16:17], 0
	s_branch .LBB0_36

; __device__ __forceinline__ unsigned xb_ld(unsigned* p)              { return __hip_atomic_load(p, __ATOMIC_RELAXED, __HIP_MEMORY_SCOPE_AGENT); }
; __device__ __forceinline__ unsigned xb_add(unsigned* p, unsigned v) { return __hip_atomic_fetch_add(p, v, __ATOMIC_RELAXED, __HIP_MEMORY_SCOPE_AGENT); }
; #define XB_SPIN(cond, bar) do { unsigned _sp = 0; while (cond) { __builtin_amdgcn_s_sleep(1); \
;     if ((++_sp & 255u) == 0u) { if (xb_ld(&(bar)[XB_TMO])) break; if (_sp > XB_SPIN_CAP) { atomicAdd(&(bar)[XB_TMO], 1u); break; } } } } while (0)
; __device__ __forceinline__ void xcd_barrier(const XcdBarrier& b) {
;     ...
;     if (old + 1u == (gen + 1u) * nloc) {
;       __builtin_amdgcn_fence(__ATOMIC_RELEASE, "agent");
;       asm volatile("s_waitcnt vmcnt(0)" ::: "memory");
;       const unsigned og = xb_add(&bar[XB_TOP], 1u);
;       const unsigned tg = og / nx;
;       if (og + 1u == (tg + 1u) * nx) xb_add(&bar[XB_TOPGEN], 1u);
;       else XB_SPIN(xb_ld(&bar[XB_TOPGEN]) == tg, bar);
.LBB0_46:
	s_andn2_saveexec_b64 s[10:11], s[10:11]
	s_cbranch_execz .LBB0_64
	v_mov_b32_e32 v5, v1
	v_sub_u32_e32 v6, v2, v1
	v_add_u32_e32 v6, -1, v6
	s_mov_b64 s[10:11], exec
	global_load_dword v7, v198, s[8:9] offset:1152 sc1
	s_waitcnt lgkmcnt(0)
	s_waitcnt vmcnt(0)
	s_mov_b32 s4, 0
	v_cmp_eq_u32_e32 vcc, v7, v6
	s_nop 1
	s_cbranch_vccnz .Lxb_idone
